# first norm phase: 8-row loop unrolled with all row loads and gain loads issued up front (one counted wait per row)
# baseline (speedup 1.0000x reference)
.LBB0_226:
	global_load_dwordx4 v[192:195], v[36:37], off
	global_load_dwordx4 v[196:199], v[36:37], off offset:1024
	global_load_dwordx4 v[244:247], v[36:37], off offset:2048
	global_load_dwordx4 v[248:251], v[36:37], off offset:3072
	v_mov_b32_e32 v252, v44
	v_mov_b32_e32 v253, v45
	global_load_dwordx4 v[96:99], v[252:253], off offset:-2048
	global_load_dwordx4 v[100:103], v[252:253], off offset:-1024
	global_load_dwordx4 v[104:107], v[252:253], off
	global_load_dwordx4 v[108:111], v[252:253], off offset:1024
	v_lshl_add_u64 v[252:253], v[252:253], 0, s[4:5]
	global_load_dwordx4 v[112:115], v[252:253], off offset:-2048
	global_load_dwordx4 v[116:119], v[252:253], off offset:-1024
	global_load_dwordx4 v[120:123], v[252:253], off
	global_load_dwordx4 v[124:127], v[252:253], off offset:1024
	v_lshl_add_u64 v[252:253], v[252:253], 0, s[4:5]
	global_load_dwordx4 v[128:131], v[252:253], off offset:-2048
	global_load_dwordx4 v[132:135], v[252:253], off offset:-1024
	global_load_dwordx4 v[136:139], v[252:253], off
	global_load_dwordx4 v[140:143], v[252:253], off offset:1024
	v_lshl_add_u64 v[252:253], v[252:253], 0, s[4:5]
	global_load_dwordx4 v[144:147], v[252:253], off offset:-2048
	global_load_dwordx4 v[148:151], v[252:253], off offset:-1024
	global_load_dwordx4 v[152:155], v[252:253], off
	global_load_dwordx4 v[156:159], v[252:253], off offset:1024
	v_lshl_add_u64 v[252:253], v[252:253], 0, s[4:5]
	global_load_dwordx4 v[160:163], v[252:253], off offset:-2048
	global_load_dwordx4 v[164:167], v[252:253], off offset:-1024
	global_load_dwordx4 v[168:171], v[252:253], off
	global_load_dwordx4 v[172:175], v[252:253], off offset:1024
	v_lshl_add_u64 v[252:253], v[252:253], 0, s[4:5]
	global_load_dwordx4 v[176:179], v[252:253], off offset:-2048
	global_load_dwordx4 v[180:183], v[252:253], off offset:-1024
	global_load_dwordx4 v[184:187], v[252:253], off
	global_load_dwordx4 v[188:191], v[252:253], off offset:1024
	v_lshl_add_u64 v[252:253], v[252:253], 0, s[4:5]
	global_load_dwordx4 v[212:215], v[252:253], off offset:-2048
	global_load_dwordx4 v[216:219], v[252:253], off offset:-1024
	global_load_dwordx4 v[220:223], v[252:253], off
	global_load_dwordx4 v[224:227], v[252:253], off offset:1024
	v_lshl_add_u64 v[252:253], v[252:253], 0, s[4:5]
	global_load_dwordx4 v[228:231], v[252:253], off offset:-2048
	global_load_dwordx4 v[232:235], v[252:253], off offset:-1024
	global_load_dwordx4 v[236:239], v[252:253], off
	global_load_dwordx4 v[240:243], v[252:253], off offset:1024
	v_lshl_add_u64 v[76:77], v[42:43], 0, s[6:7]
	v_add_co_u32_e64 v76, s[0:1], s10, v76
	s_add_u32 s6, s6, 0x800
	s_nop 0
	v_addc_co_u32_e64 v77, s[0:1], 0, v77, s[0:1]
	s_addc_u32 s7, s7, 0
	v_lshl_add_u64 v[44:45], v[44:45], 0, s[4:5]
	s_cmpk_eq_i32 s6, 0x4000
	s_waitcnt vmcnt(28)
	v_pk_mul_f32 v[78:79], v[98:99], v[98:99]
	v_pk_mul_f32 v[80:81], v[96:97], v[96:97]
	v_pk_mul_f32 v[82:83], v[102:103], v[102:103]
	v_pk_mul_f32 v[84:85], v[100:101], v[100:101]
	v_pk_mov_b32 v[90:91], v[80:81], v[78:79] op_sel:[1, 0]
	v_mov_b32_e32 v81, v79
	v_pk_mov_b32 v[78:79], v[84:85], v[82:83] op_sel:[1, 0]
	v_mov_b32_e32 v85, v83
	v_mul_f32_e32 v89, v108, v108
	v_mul_f32_e32 v86, v105, v105
	v_mul_f32_e32 v88, v107, v107
	v_pk_add_f32 v[80:81], v[90:91], v[80:81]
	v_pk_add_f32 v[78:79], v[78:79], v[84:85]
	v_mul_f32_e32 v92, v109, v109
	v_mul_f32_e32 v93, v110, v110
	v_mul_f32_e32 v94, v111, v111
	v_pk_fma_f32 v[82:83], v[104:105], v[104:105], v[86:87] op_sel_hi:[1, 1, 0]
	v_pk_fma_f32 v[86:87], v[106:107], v[106:107], v[88:89] op_sel_hi:[1, 1, 0]
	v_pk_add_f32 v[80:81], v[80:81], v[80:81] op_sel:[0, 1] op_sel_hi:[1, 0]
	v_pk_add_f32 v[78:79], v[78:79], v[78:79] op_sel:[0, 1] op_sel_hi:[1, 0]
	v_mov_b32_e32 v83, v93
	v_mov_b32_e32 v87, v94
	v_mov_b32_e32 v81, v89
	v_mov_b32_e32 v79, v92
	v_pk_add_f32 v[82:83], v[82:83], v[86:87]
	v_pk_add_f32 v[78:79], v[80:81], v[78:79]
	s_nop 0
	v_pk_add_f32 v[78:79], v[78:79], v[82:83]
	s_nop 0
	v_add_f32_e32 v78, v78, v79
	s_waitcnt lgkmcnt(0)
	s_nop 1
	v_add_f32_dpp v78, v78, v78 quad_perm:[1, 0, 3, 2] row_mask:0xf bank_mask:0xf
	s_nop 1
	v_add_f32_dpp v78, v78, v78 quad_perm:[2, 3, 0, 1] row_mask:0xf bank_mask:0xf
	s_nop 1
	v_add_f32_dpp v78, v78, v78 row_half_mirror row_mask:0xf bank_mask:0xf
	s_nop 1
	v_add_f32_dpp v78, v78, v78 row_mirror row_mask:0xf bank_mask:0xf
	ds_bpermute_b32 v79, v51, v78
	s_waitcnt lgkmcnt(0)
	v_add_f32_e32 v78, v78, v79
	v_mov_b32_e32 v79, v78
	s_nop 1
	v_permlane32_swap_b32_e32 v79, v78
	v_add_f32_e32 v78, v78, v79
	v_fmamk_f32 v78, v78, 0x3a800000, v55
	v_mul_f32_e32 v79, 0x4b800000, v78
	v_cmp_gt_f32_e64 s[0:1], s9, v78
	s_nop 1
	v_cndmask_b32_e64 v78, v78, v79, s[0:1]
	v_rsq_f32_e32 v78, v78
	s_nop 0
	v_mul_f32_e32 v79, 0x45800000, v78
	v_cndmask_b32_e64 v78, v78, v79, s[0:1]
	v_pk_mul_f32 v[98:99], v[98:99], v[78:79] op_sel_hi:[1, 0]
	v_pk_mul_f32 v[96:97], v[96:97], v[78:79] op_sel_hi:[1, 0]
	v_pk_mul_f32 v[98:99], v[194:195], v[98:99]
	v_pk_mul_f32 v[96:97], v[192:193], v[96:97]
	v_pk_fma_f32 v[98:99], v[10:11], v[98:99], v[2:3]
	v_pk_fma_f32 v[96:97], v[8:9], v[96:97], v[0:1]
	v_pk_mul_f32 v[102:103], v[102:103], v[78:79] op_sel_hi:[1, 0]
	v_cvt_pk_bf16_f32 v96, v96, v97
	v_cvt_pk_bf16_f32 v97, v98, v99
	global_store_dwordx2 v[76:77], v[96:97], off
	v_pk_mul_f32 v[100:101], v[100:101], v[78:79] op_sel_hi:[1, 0]
	v_pk_mul_f32 v[98:99], v[198:199], v[102:103]
	v_pk_mul_f32 v[96:97], v[196:197], v[100:101]
	v_pk_fma_f32 v[98:99], v[14:15], v[98:99], v[6:7]
	v_pk_fma_f32 v[96:97], v[12:13], v[96:97], v[4:5]
	v_pk_mul_f32 v[100:101], v[106:107], v[78:79] op_sel_hi:[1, 0]
	v_cvt_pk_bf16_f32 v96, v96, v97
	v_cvt_pk_bf16_f32 v97, v98, v99
	global_store_dwordx2 v[76:77], v[96:97], off offset:512
	v_pk_mul_f32 v[102:103], v[104:105], v[78:79] op_sel_hi:[1, 0]
	v_pk_mul_f32 v[98:99], v[246:247], v[100:101]
	v_pk_mul_f32 v[96:97], v[244:245], v[102:103]
	v_pk_fma_f32 v[98:99], v[26:27], v[98:99], v[18:19]
	v_pk_fma_f32 v[96:97], v[24:25], v[96:97], v[16:17]
	v_pk_mul_f32 v[100:101], v[110:111], v[78:79] op_sel_hi:[1, 0]
	v_cvt_pk_bf16_f32 v96, v96, v97
	v_cvt_pk_bf16_f32 v97, v98, v99
	global_store_dwordx2 v[76:77], v[96:97], off offset:1024
	v_pk_mul_f32 v[102:103], v[108:109], v[78:79] op_sel_hi:[1, 0]
	v_pk_mul_f32 v[98:99], v[250:251], v[100:101]
	v_pk_mul_f32 v[96:97], v[248:249], v[102:103]
	v_pk_fma_f32 v[98:99], v[30:31], v[98:99], v[22:23]
	v_pk_fma_f32 v[96:97], v[28:29], v[96:97], v[20:21]
	s_nop 0
	v_cvt_pk_bf16_f32 v96, v96, v97
	v_cvt_pk_bf16_f32 v97, v98, v99
	global_store_dwordx2 v[76:77], v[96:97], off offset:1536
	v_lshl_add_u64 v[76:77], v[42:43], 0, s[6:7]
	v_add_co_u32_e64 v76, s[0:1], s10, v76
	s_add_u32 s6, s6, 0x800
	s_nop 0
	v_addc_co_u32_e64 v77, s[0:1], 0, v77, s[0:1]
	s_addc_u32 s7, s7, 0
	v_lshl_add_u64 v[44:45], v[44:45], 0, s[4:5]
	s_cmpk_eq_i32 s6, 0x4000
	s_waitcnt vmcnt(28)
	v_pk_mul_f32 v[78:79], v[114:115], v[114:115]
	v_pk_mul_f32 v[80:81], v[112:113], v[112:113]
	v_pk_mul_f32 v[82:83], v[118:119], v[118:119]
	v_pk_mul_f32 v[84:85], v[116:117], v[116:117]
	v_pk_mov_b32 v[90:91], v[80:81], v[78:79] op_sel:[1, 0]
	v_mov_b32_e32 v81, v79
	v_pk_mov_b32 v[78:79], v[84:85], v[82:83] op_sel:[1, 0]
	v_mov_b32_e32 v85, v83
	v_mul_f32_e32 v89, v124, v124
	v_mul_f32_e32 v86, v121, v121
	v_mul_f32_e32 v88, v123, v123
	v_pk_add_f32 v[80:81], v[90:91], v[80:81]
	v_pk_add_f32 v[78:79], v[78:79], v[84:85]
	v_mul_f32_e32 v92, v125, v125
	v_mul_f32_e32 v93, v126, v126
	v_mul_f32_e32 v94, v127, v127
	v_pk_fma_f32 v[82:83], v[120:121], v[120:121], v[86:87] op_sel_hi:[1, 1, 0]
	v_pk_fma_f32 v[86:87], v[122:123], v[122:123], v[88:89] op_sel_hi:[1, 1, 0]
	v_pk_add_f32 v[80:81], v[80:81], v[80:81] op_sel:[0, 1] op_sel_hi:[1, 0]
	v_pk_add_f32 v[78:79], v[78:79], v[78:79] op_sel:[0, 1] op_sel_hi:[1, 0]
	v_mov_b32_e32 v83, v93
	v_mov_b32_e32 v87, v94
	v_mov_b32_e32 v81, v89
	v_mov_b32_e32 v79, v92
	v_pk_add_f32 v[82:83], v[82:83], v[86:87]
	v_pk_add_f32 v[78:79], v[80:81], v[78:79]
	s_nop 0
	v_pk_add_f32 v[78:79], v[78:79], v[82:83]
	s_nop 0
	v_add_f32_e32 v78, v78, v79
	s_waitcnt lgkmcnt(0)
	s_nop 1
	v_add_f32_dpp v78, v78, v78 quad_perm:[1, 0, 3, 2] row_mask:0xf bank_mask:0xf
	s_nop 1
	v_add_f32_dpp v78, v78, v78 quad_perm:[2, 3, 0, 1] row_mask:0xf bank_mask:0xf
	s_nop 1
	v_add_f32_dpp v78, v78, v78 row_half_mirror row_mask:0xf bank_mask:0xf
	s_nop 1
	v_add_f32_dpp v78, v78, v78 row_mirror row_mask:0xf bank_mask:0xf
	ds_bpermute_b32 v79, v51, v78
	s_waitcnt lgkmcnt(0)
	v_add_f32_e32 v78, v78, v79
	v_mov_b32_e32 v79, v78
	s_nop 1
	v_permlane32_swap_b32_e32 v79, v78
	v_add_f32_e32 v78, v78, v79
	v_fmamk_f32 v78, v78, 0x3a800000, v55
	v_mul_f32_e32 v79, 0x4b800000, v78
	v_cmp_gt_f32_e64 s[0:1], s9, v78
	s_nop 1
	v_cndmask_b32_e64 v78, v78, v79, s[0:1]
	v_rsq_f32_e32 v78, v78
	s_nop 0
	v_mul_f32_e32 v79, 0x45800000, v78
	v_cndmask_b32_e64 v78, v78, v79, s[0:1]
	v_pk_mul_f32 v[114:115], v[114:115], v[78:79] op_sel_hi:[1, 0]
	v_pk_mul_f32 v[112:113], v[112:113], v[78:79] op_sel_hi:[1, 0]
	v_pk_mul_f32 v[114:115], v[194:195], v[114:115]
	v_pk_mul_f32 v[112:113], v[192:193], v[112:113]
	v_pk_fma_f32 v[114:115], v[10:11], v[114:115], v[2:3]
	v_pk_fma_f32 v[112:113], v[8:9], v[112:113], v[0:1]
	v_pk_mul_f32 v[118:119], v[118:119], v[78:79] op_sel_hi:[1, 0]
	v_cvt_pk_bf16_f32 v112, v112, v113
	v_cvt_pk_bf16_f32 v113, v114, v115
	global_store_dwordx2 v[76:77], v[112:113], off
	v_pk_mul_f32 v[116:117], v[116:117], v[78:79] op_sel_hi:[1, 0]
	v_pk_mul_f32 v[114:115], v[198:199], v[118:119]
	v_pk_mul_f32 v[112:113], v[196:197], v[116:117]
	v_pk_fma_f32 v[114:115], v[14:15], v[114:115], v[6:7]
	v_pk_fma_f32 v[112:113], v[12:13], v[112:113], v[4:5]
	v_pk_mul_f32 v[116:117], v[122:123], v[78:79] op_sel_hi:[1, 0]
	v_cvt_pk_bf16_f32 v112, v112, v113
	v_cvt_pk_bf16_f32 v113, v114, v115
	global_store_dwordx2 v[76:77], v[112:113], off offset:512
	v_pk_mul_f32 v[118:119], v[120:121], v[78:79] op_sel_hi:[1, 0]
	v_pk_mul_f32 v[114:115], v[246:247], v[116:117]
	v_pk_mul_f32 v[112:113], v[244:245], v[118:119]
	v_pk_fma_f32 v[114:115], v[26:27], v[114:115], v[18:19]
	v_pk_fma_f32 v[112:113], v[24:25], v[112:113], v[16:17]
	v_pk_mul_f32 v[116:117], v[126:127], v[78:79] op_sel_hi:[1, 0]
	v_cvt_pk_bf16_f32 v112, v112, v113
	v_cvt_pk_bf16_f32 v113, v114, v115
	global_store_dwordx2 v[76:77], v[112:113], off offset:1024
	v_pk_mul_f32 v[118:119], v[124:125], v[78:79] op_sel_hi:[1, 0]
	v_pk_mul_f32 v[114:115], v[250:251], v[116:117]
	v_pk_mul_f32 v[112:113], v[248:249], v[118:119]
	v_pk_fma_f32 v[114:115], v[30:31], v[114:115], v[22:23]
	v_pk_fma_f32 v[112:113], v[28:29], v[112:113], v[20:21]
	s_nop 0
	v_cvt_pk_bf16_f32 v112, v112, v113
	v_cvt_pk_bf16_f32 v113, v114, v115
	global_store_dwordx2 v[76:77], v[112:113], off offset:1536
	v_lshl_add_u64 v[76:77], v[42:43], 0, s[6:7]
	v_add_co_u32_e64 v76, s[0:1], s10, v76
	s_add_u32 s6, s6, 0x800
	s_nop 0
	v_addc_co_u32_e64 v77, s[0:1], 0, v77, s[0:1]
	s_addc_u32 s7, s7, 0
	v_lshl_add_u64 v[44:45], v[44:45], 0, s[4:5]
	s_cmpk_eq_i32 s6, 0x4000
	s_waitcnt vmcnt(28)
	v_pk_mul_f32 v[78:79], v[130:131], v[130:131]
	v_pk_mul_f32 v[80:81], v[128:129], v[128:129]
	v_pk_mul_f32 v[82:83], v[134:135], v[134:135]
	v_pk_mul_f32 v[84:85], v[132:133], v[132:133]
	v_pk_mov_b32 v[90:91], v[80:81], v[78:79] op_sel:[1, 0]
	v_mov_b32_e32 v81, v79
	v_pk_mov_b32 v[78:79], v[84:85], v[82:83] op_sel:[1, 0]
	v_mov_b32_e32 v85, v83
	v_mul_f32_e32 v89, v140, v140
	v_mul_f32_e32 v86, v137, v137
	v_mul_f32_e32 v88, v139, v139
	v_pk_add_f32 v[80:81], v[90:91], v[80:81]
	v_pk_add_f32 v[78:79], v[78:79], v[84:85]
	v_mul_f32_e32 v92, v141, v141
	v_mul_f32_e32 v93, v142, v142
	v_mul_f32_e32 v94, v143, v143
	v_pk_fma_f32 v[82:83], v[136:137], v[136:137], v[86:87] op_sel_hi:[1, 1, 0]
	v_pk_fma_f32 v[86:87], v[138:139], v[138:139], v[88:89] op_sel_hi:[1, 1, 0]
	v_pk_add_f32 v[80:81], v[80:81], v[80:81] op_sel:[0, 1] op_sel_hi:[1, 0]
	v_pk_add_f32 v[78:79], v[78:79], v[78:79] op_sel:[0, 1] op_sel_hi:[1, 0]
	v_mov_b32_e32 v83, v93
	v_mov_b32_e32 v87, v94
	v_mov_b32_e32 v81, v89
	v_mov_b32_e32 v79, v92
	v_pk_add_f32 v[82:83], v[82:83], v[86:87]
	v_pk_add_f32 v[78:79], v[80:81], v[78:79]
	s_nop 0
	v_pk_add_f32 v[78:79], v[78:79], v[82:83]
	s_nop 0
	v_add_f32_e32 v78, v78, v79
	s_waitcnt lgkmcnt(0)
	s_nop 1
	v_add_f32_dpp v78, v78, v78 quad_perm:[1, 0, 3, 2] row_mask:0xf bank_mask:0xf
	s_nop 1
	v_add_f32_dpp v78, v78, v78 quad_perm:[2, 3, 0, 1] row_mask:0xf bank_mask:0xf
	s_nop 1
	v_add_f32_dpp v78, v78, v78 row_half_mirror row_mask:0xf bank_mask:0xf
	s_nop 1
	v_add_f32_dpp v78, v78, v78 row_mirror row_mask:0xf bank_mask:0xf
	ds_bpermute_b32 v79, v51, v78
	s_waitcnt lgkmcnt(0)
	v_add_f32_e32 v78, v78, v79
	v_mov_b32_e32 v79, v78
	s_nop 1
	v_permlane32_swap_b32_e32 v79, v78
	v_add_f32_e32 v78, v78, v79
	v_fmamk_f32 v78, v78, 0x3a800000, v55
	v_mul_f32_e32 v79, 0x4b800000, v78
	v_cmp_gt_f32_e64 s[0:1], s9, v78
	s_nop 1
	v_cndmask_b32_e64 v78, v78, v79, s[0:1]
	v_rsq_f32_e32 v78, v78
	s_nop 0
	v_mul_f32_e32 v79, 0x45800000, v78
	v_cndmask_b32_e64 v78, v78, v79, s[0:1]
	v_pk_mul_f32 v[130:131], v[130:131], v[78:79] op_sel_hi:[1, 0]
	v_pk_mul_f32 v[128:129], v[128:129], v[78:79] op_sel_hi:[1, 0]
	v_pk_mul_f32 v[130:131], v[194:195], v[130:131]
	v_pk_mul_f32 v[128:129], v[192:193], v[128:129]
	v_pk_fma_f32 v[130:131], v[10:11], v[130:131], v[2:3]
	v_pk_fma_f32 v[128:129], v[8:9], v[128:129], v[0:1]
	v_pk_mul_f32 v[134:135], v[134:135], v[78:79] op_sel_hi:[1, 0]
	v_cvt_pk_bf16_f32 v128, v128, v129
	v_cvt_pk_bf16_f32 v129, v130, v131
	global_store_dwordx2 v[76:77], v[128:129], off
	v_pk_mul_f32 v[132:133], v[132:133], v[78:79] op_sel_hi:[1, 0]
	v_pk_mul_f32 v[130:131], v[198:199], v[134:135]
	v_pk_mul_f32 v[128:129], v[196:197], v[132:133]
	v_pk_fma_f32 v[130:131], v[14:15], v[130:131], v[6:7]
	v_pk_fma_f32 v[128:129], v[12:13], v[128:129], v[4:5]
	v_pk_mul_f32 v[132:133], v[138:139], v[78:79] op_sel_hi:[1, 0]
	v_cvt_pk_bf16_f32 v128, v128, v129
	v_cvt_pk_bf16_f32 v129, v130, v131
	global_store_dwordx2 v[76:77], v[128:129], off offset:512
	v_pk_mul_f32 v[134:135], v[136:137], v[78:79] op_sel_hi:[1, 0]
	v_pk_mul_f32 v[130:131], v[246:247], v[132:133]
	v_pk_mul_f32 v[128:129], v[244:245], v[134:135]
	v_pk_fma_f32 v[130:131], v[26:27], v[130:131], v[18:19]
	v_pk_fma_f32 v[128:129], v[24:25], v[128:129], v[16:17]
	v_pk_mul_f32 v[132:133], v[142:143], v[78:79] op_sel_hi:[1, 0]
	v_cvt_pk_bf16_f32 v128, v128, v129
	v_cvt_pk_bf16_f32 v129, v130, v131
	global_store_dwordx2 v[76:77], v[128:129], off offset:1024
	v_pk_mul_f32 v[134:135], v[140:141], v[78:79] op_sel_hi:[1, 0]
	v_pk_mul_f32 v[130:131], v[250:251], v[132:133]
	v_pk_mul_f32 v[128:129], v[248:249], v[134:135]
	v_pk_fma_f32 v[130:131], v[30:31], v[130:131], v[22:23]
	v_pk_fma_f32 v[128:129], v[28:29], v[128:129], v[20:21]
	s_nop 0
	v_cvt_pk_bf16_f32 v128, v128, v129
	v_cvt_pk_bf16_f32 v129, v130, v131
	global_store_dwordx2 v[76:77], v[128:129], off offset:1536
	v_lshl_add_u64 v[76:77], v[42:43], 0, s[6:7]
	v_add_co_u32_e64 v76, s[0:1], s10, v76
	s_add_u32 s6, s6, 0x800
	s_nop 0
	v_addc_co_u32_e64 v77, s[0:1], 0, v77, s[0:1]
	s_addc_u32 s7, s7, 0
	v_lshl_add_u64 v[44:45], v[44:45], 0, s[4:5]
	s_cmpk_eq_i32 s6, 0x4000
	s_waitcnt vmcnt(28)
	v_pk_mul_f32 v[78:79], v[146:147], v[146:147]
	v_pk_mul_f32 v[80:81], v[144:145], v[144:145]
	v_pk_mul_f32 v[82:83], v[150:151], v[150:151]
	v_pk_mul_f32 v[84:85], v[148:149], v[148:149]
	v_pk_mov_b32 v[90:91], v[80:81], v[78:79] op_sel:[1, 0]
	v_mov_b32_e32 v81, v79
	v_pk_mov_b32 v[78:79], v[84:85], v[82:83] op_sel:[1, 0]
	v_mov_b32_e32 v85, v83
	v_mul_f32_e32 v89, v156, v156
	v_mul_f32_e32 v86, v153, v153
	v_mul_f32_e32 v88, v155, v155
	v_pk_add_f32 v[80:81], v[90:91], v[80:81]
	v_pk_add_f32 v[78:79], v[78:79], v[84:85]
	v_mul_f32_e32 v92, v157, v157
	v_mul_f32_e32 v93, v158, v158
	v_mul_f32_e32 v94, v159, v159
	v_pk_fma_f32 v[82:83], v[152:153], v[152:153], v[86:87] op_sel_hi:[1, 1, 0]
	v_pk_fma_f32 v[86:87], v[154:155], v[154:155], v[88:89] op_sel_hi:[1, 1, 0]
	v_pk_add_f32 v[80:81], v[80:81], v[80:81] op_sel:[0, 1] op_sel_hi:[1, 0]
	v_pk_add_f32 v[78:79], v[78:79], v[78:79] op_sel:[0, 1] op_sel_hi:[1, 0]
	v_mov_b32_e32 v83, v93
	v_mov_b32_e32 v87, v94
	v_mov_b32_e32 v81, v89
	v_mov_b32_e32 v79, v92
	v_pk_add_f32 v[82:83], v[82:83], v[86:87]
	v_pk_add_f32 v[78:79], v[80:81], v[78:79]
	s_nop 0
	v_pk_add_f32 v[78:79], v[78:79], v[82:83]
	s_nop 0
	v_add_f32_e32 v78, v78, v79
	s_waitcnt lgkmcnt(0)
	s_nop 1
	v_add_f32_dpp v78, v78, v78 quad_perm:[1, 0, 3, 2] row_mask:0xf bank_mask:0xf
	s_nop 1
	v_add_f32_dpp v78, v78, v78 quad_perm:[2, 3, 0, 1] row_mask:0xf bank_mask:0xf
	s_nop 1
	v_add_f32_dpp v78, v78, v78 row_half_mirror row_mask:0xf bank_mask:0xf
	s_nop 1
	v_add_f32_dpp v78, v78, v78 row_mirror row_mask:0xf bank_mask:0xf
	ds_bpermute_b32 v79, v51, v78
	s_waitcnt lgkmcnt(0)
	v_add_f32_e32 v78, v78, v79
	v_mov_b32_e32 v79, v78
	s_nop 1
	v_permlane32_swap_b32_e32 v79, v78
	v_add_f32_e32 v78, v78, v79
	v_fmamk_f32 v78, v78, 0x3a800000, v55
	v_mul_f32_e32 v79, 0x4b800000, v78
	v_cmp_gt_f32_e64 s[0:1], s9, v78
	s_nop 1
	v_cndmask_b32_e64 v78, v78, v79, s[0:1]
	v_rsq_f32_e32 v78, v78
	s_nop 0
	v_mul_f32_e32 v79, 0x45800000, v78
	v_cndmask_b32_e64 v78, v78, v79, s[0:1]
	v_pk_mul_f32 v[146:147], v[146:147], v[78:79] op_sel_hi:[1, 0]
	v_pk_mul_f32 v[144:145], v[144:145], v[78:79] op_sel_hi:[1, 0]
	v_pk_mul_f32 v[146:147], v[194:195], v[146:147]
	v_pk_mul_f32 v[144:145], v[192:193], v[144:145]
	v_pk_fma_f32 v[146:147], v[10:11], v[146:147], v[2:3]
	v_pk_fma_f32 v[144:145], v[8:9], v[144:145], v[0:1]
	v_pk_mul_f32 v[150:151], v[150:151], v[78:79] op_sel_hi:[1, 0]
	v_cvt_pk_bf16_f32 v144, v144, v145
	v_cvt_pk_bf16_f32 v145, v146, v147
	global_store_dwordx2 v[76:77], v[144:145], off
	v_pk_mul_f32 v[148:149], v[148:149], v[78:79] op_sel_hi:[1, 0]
	v_pk_mul_f32 v[146:147], v[198:199], v[150:151]
	v_pk_mul_f32 v[144:145], v[196:197], v[148:149]
	v_pk_fma_f32 v[146:147], v[14:15], v[146:147], v[6:7]
	v_pk_fma_f32 v[144:145], v[12:13], v[144:145], v[4:5]
	v_pk_mul_f32 v[148:149], v[154:155], v[78:79] op_sel_hi:[1, 0]
	v_cvt_pk_bf16_f32 v144, v144, v145
	v_cvt_pk_bf16_f32 v145, v146, v147
	global_store_dwordx2 v[76:77], v[144:145], off offset:512
	v_pk_mul_f32 v[150:151], v[152:153], v[78:79] op_sel_hi:[1, 0]
	v_pk_mul_f32 v[146:147], v[246:247], v[148:149]
	v_pk_mul_f32 v[144:145], v[244:245], v[150:151]
	v_pk_fma_f32 v[146:147], v[26:27], v[146:147], v[18:19]
	v_pk_fma_f32 v[144:145], v[24:25], v[144:145], v[16:17]
	v_pk_mul_f32 v[148:149], v[158:159], v[78:79] op_sel_hi:[1, 0]
	v_cvt_pk_bf16_f32 v144, v144, v145
	v_cvt_pk_bf16_f32 v145, v146, v147
	global_store_dwordx2 v[76:77], v[144:145], off offset:1024
	v_pk_mul_f32 v[150:151], v[156:157], v[78:79] op_sel_hi:[1, 0]
	v_pk_mul_f32 v[146:147], v[250:251], v[148:149]
	v_pk_mul_f32 v[144:145], v[248:249], v[150:151]
	v_pk_fma_f32 v[146:147], v[30:31], v[146:147], v[22:23]
	v_pk_fma_f32 v[144:145], v[28:29], v[144:145], v[20:21]
	s_nop 0
	v_cvt_pk_bf16_f32 v144, v144, v145
	v_cvt_pk_bf16_f32 v145, v146, v147
	global_store_dwordx2 v[76:77], v[144:145], off offset:1536
	v_lshl_add_u64 v[76:77], v[42:43], 0, s[6:7]
	v_add_co_u32_e64 v76, s[0:1], s10, v76
	s_add_u32 s6, s6, 0x800
	s_nop 0
	v_addc_co_u32_e64 v77, s[0:1], 0, v77, s[0:1]
	s_addc_u32 s7, s7, 0
	v_lshl_add_u64 v[44:45], v[44:45], 0, s[4:5]
	s_cmpk_eq_i32 s6, 0x4000
	s_waitcnt vmcnt(28)
	v_pk_mul_f32 v[78:79], v[162:163], v[162:163]
	v_pk_mul_f32 v[80:81], v[160:161], v[160:161]
	v_pk_mul_f32 v[82:83], v[166:167], v[166:167]
	v_pk_mul_f32 v[84:85], v[164:165], v[164:165]
	v_pk_mov_b32 v[90:91], v[80:81], v[78:79] op_sel:[1, 0]
	v_mov_b32_e32 v81, v79
	v_pk_mov_b32 v[78:79], v[84:85], v[82:83] op_sel:[1, 0]
	v_mov_b32_e32 v85, v83
	v_mul_f32_e32 v89, v172, v172
	v_mul_f32_e32 v86, v169, v169
	v_mul_f32_e32 v88, v171, v171
	v_pk_add_f32 v[80:81], v[90:91], v[80:81]
	v_pk_add_f32 v[78:79], v[78:79], v[84:85]
	v_mul_f32_e32 v92, v173, v173
	v_mul_f32_e32 v93, v174, v174
	v_mul_f32_e32 v94, v175, v175
	v_pk_fma_f32 v[82:83], v[168:169], v[168:169], v[86:87] op_sel_hi:[1, 1, 0]
	v_pk_fma_f32 v[86:87], v[170:171], v[170:171], v[88:89] op_sel_hi:[1, 1, 0]
	v_pk_add_f32 v[80:81], v[80:81], v[80:81] op_sel:[0, 1] op_sel_hi:[1, 0]
	v_pk_add_f32 v[78:79], v[78:79], v[78:79] op_sel:[0, 1] op_sel_hi:[1, 0]
	v_mov_b32_e32 v83, v93
	v_mov_b32_e32 v87, v94
	v_mov_b32_e32 v81, v89
	v_mov_b32_e32 v79, v92
	v_pk_add_f32 v[82:83], v[82:83], v[86:87]
	v_pk_add_f32 v[78:79], v[80:81], v[78:79]
	s_nop 0
	v_pk_add_f32 v[78:79], v[78:79], v[82:83]
	s_nop 0
	v_add_f32_e32 v78, v78, v79
	s_waitcnt lgkmcnt(0)
	s_nop 1
	v_add_f32_dpp v78, v78, v78 quad_perm:[1, 0, 3, 2] row_mask:0xf bank_mask:0xf
	s_nop 1
	v_add_f32_dpp v78, v78, v78 quad_perm:[2, 3, 0, 1] row_mask:0xf bank_mask:0xf
	s_nop 1
	v_add_f32_dpp v78, v78, v78 row_half_mirror row_mask:0xf bank_mask:0xf
	s_nop 1
	v_add_f32_dpp v78, v78, v78 row_mirror row_mask:0xf bank_mask:0xf
	ds_bpermute_b32 v79, v51, v78
	s_waitcnt lgkmcnt(0)
	v_add_f32_e32 v78, v78, v79
	v_mov_b32_e32 v79, v78
	s_nop 1
	v_permlane32_swap_b32_e32 v79, v78
	v_add_f32_e32 v78, v78, v79
	v_fmamk_f32 v78, v78, 0x3a800000, v55
	v_mul_f32_e32 v79, 0x4b800000, v78
	v_cmp_gt_f32_e64 s[0:1], s9, v78
	s_nop 1
	v_cndmask_b32_e64 v78, v78, v79, s[0:1]
	v_rsq_f32_e32 v78, v78
	s_nop 0
	v_mul_f32_e32 v79, 0x45800000, v78
	v_cndmask_b32_e64 v78, v78, v79, s[0:1]
	v_pk_mul_f32 v[162:163], v[162:163], v[78:79] op_sel_hi:[1, 0]
	v_pk_mul_f32 v[160:161], v[160:161], v[78:79] op_sel_hi:[1, 0]
	v_pk_mul_f32 v[162:163], v[194:195], v[162:163]
	v_pk_mul_f32 v[160:161], v[192:193], v[160:161]
	v_pk_fma_f32 v[162:163], v[10:11], v[162:163], v[2:3]
	v_pk_fma_f32 v[160:161], v[8:9], v[160:161], v[0:1]
	v_pk_mul_f32 v[166:167], v[166:167], v[78:79] op_sel_hi:[1, 0]
	v_cvt_pk_bf16_f32 v160, v160, v161
	v_cvt_pk_bf16_f32 v161, v162, v163
	global_store_dwordx2 v[76:77], v[160:161], off
	v_pk_mul_f32 v[164:165], v[164:165], v[78:79] op_sel_hi:[1, 0]
	v_pk_mul_f32 v[162:163], v[198:199], v[166:167]
	v_pk_mul_f32 v[160:161], v[196:197], v[164:165]
	v_pk_fma_f32 v[162:163], v[14:15], v[162:163], v[6:7]
	v_pk_fma_f32 v[160:161], v[12:13], v[160:161], v[4:5]
	v_pk_mul_f32 v[164:165], v[170:171], v[78:79] op_sel_hi:[1, 0]
	v_cvt_pk_bf16_f32 v160, v160, v161
	v_cvt_pk_bf16_f32 v161, v162, v163
	global_store_dwordx2 v[76:77], v[160:161], off offset:512
	v_pk_mul_f32 v[166:167], v[168:169], v[78:79] op_sel_hi:[1, 0]
	v_pk_mul_f32 v[162:163], v[246:247], v[164:165]
	v_pk_mul_f32 v[160:161], v[244:245], v[166:167]
	v_pk_fma_f32 v[162:163], v[26:27], v[162:163], v[18:19]
	v_pk_fma_f32 v[160:161], v[24:25], v[160:161], v[16:17]
	v_pk_mul_f32 v[164:165], v[174:175], v[78:79] op_sel_hi:[1, 0]
	v_cvt_pk_bf16_f32 v160, v160, v161
	v_cvt_pk_bf16_f32 v161, v162, v163
	global_store_dwordx2 v[76:77], v[160:161], off offset:1024
	v_pk_mul_f32 v[166:167], v[172:173], v[78:79] op_sel_hi:[1, 0]
	v_pk_mul_f32 v[162:163], v[250:251], v[164:165]
	v_pk_mul_f32 v[160:161], v[248:249], v[166:167]
	v_pk_fma_f32 v[162:163], v[30:31], v[162:163], v[22:23]
	v_pk_fma_f32 v[160:161], v[28:29], v[160:161], v[20:21]
	s_nop 0
	v_cvt_pk_bf16_f32 v160, v160, v161
	v_cvt_pk_bf16_f32 v161, v162, v163
	global_store_dwordx2 v[76:77], v[160:161], off offset:1536
	v_lshl_add_u64 v[76:77], v[42:43], 0, s[6:7]
	v_add_co_u32_e64 v76, s[0:1], s10, v76
	s_add_u32 s6, s6, 0x800
	s_nop 0
	v_addc_co_u32_e64 v77, s[0:1], 0, v77, s[0:1]
	s_addc_u32 s7, s7, 0
	v_lshl_add_u64 v[44:45], v[44:45], 0, s[4:5]
	s_cmpk_eq_i32 s6, 0x4000
	s_waitcnt vmcnt(28)
	v_pk_mul_f32 v[78:79], v[178:179], v[178:179]
	v_pk_mul_f32 v[80:81], v[176:177], v[176:177]
	v_pk_mul_f32 v[82:83], v[182:183], v[182:183]
	v_pk_mul_f32 v[84:85], v[180:181], v[180:181]
	v_pk_mov_b32 v[90:91], v[80:81], v[78:79] op_sel:[1, 0]
	v_mov_b32_e32 v81, v79
	v_pk_mov_b32 v[78:79], v[84:85], v[82:83] op_sel:[1, 0]
	v_mov_b32_e32 v85, v83
	v_mul_f32_e32 v89, v188, v188
	v_mul_f32_e32 v86, v185, v185
	v_mul_f32_e32 v88, v187, v187
	v_pk_add_f32 v[80:81], v[90:91], v[80:81]
	v_pk_add_f32 v[78:79], v[78:79], v[84:85]
	v_mul_f32_e32 v92, v189, v189
	v_mul_f32_e32 v93, v190, v190
	v_mul_f32_e32 v94, v191, v191
	v_pk_fma_f32 v[82:83], v[184:185], v[184:185], v[86:87] op_sel_hi:[1, 1, 0]
	v_pk_fma_f32 v[86:87], v[186:187], v[186:187], v[88:89] op_sel_hi:[1, 1, 0]
	v_pk_add_f32 v[80:81], v[80:81], v[80:81] op_sel:[0, 1] op_sel_hi:[1, 0]
	v_pk_add_f32 v[78:79], v[78:79], v[78:79] op_sel:[0, 1] op_sel_hi:[1, 0]
	v_mov_b32_e32 v83, v93
	v_mov_b32_e32 v87, v94
	v_mov_b32_e32 v81, v89
	v_mov_b32_e32 v79, v92
	v_pk_add_f32 v[82:83], v[82:83], v[86:87]
	v_pk_add_f32 v[78:79], v[80:81], v[78:79]
	s_nop 0
	v_pk_add_f32 v[78:79], v[78:79], v[82:83]
	s_nop 0
	v_add_f32_e32 v78, v78, v79
	s_waitcnt lgkmcnt(0)
	s_nop 1
	v_add_f32_dpp v78, v78, v78 quad_perm:[1, 0, 3, 2] row_mask:0xf bank_mask:0xf
	s_nop 1
	v_add_f32_dpp v78, v78, v78 quad_perm:[2, 3, 0, 1] row_mask:0xf bank_mask:0xf
	s_nop 1
	v_add_f32_dpp v78, v78, v78 row_half_mirror row_mask:0xf bank_mask:0xf
	s_nop 1
	v_add_f32_dpp v78, v78, v78 row_mirror row_mask:0xf bank_mask:0xf
	ds_bpermute_b32 v79, v51, v78
	s_waitcnt lgkmcnt(0)
	v_add_f32_e32 v78, v78, v79
	v_mov_b32_e32 v79, v78
	s_nop 1
	v_permlane32_swap_b32_e32 v79, v78
	v_add_f32_e32 v78, v78, v79
	v_fmamk_f32 v78, v78, 0x3a800000, v55
	v_mul_f32_e32 v79, 0x4b800000, v78
	v_cmp_gt_f32_e64 s[0:1], s9, v78
	s_nop 1
	v_cndmask_b32_e64 v78, v78, v79, s[0:1]
	v_rsq_f32_e32 v78, v78
	s_nop 0
	v_mul_f32_e32 v79, 0x45800000, v78
	v_cndmask_b32_e64 v78, v78, v79, s[0:1]
	v_pk_mul_f32 v[178:179], v[178:179], v[78:79] op_sel_hi:[1, 0]
	v_pk_mul_f32 v[176:177], v[176:177], v[78:79] op_sel_hi:[1, 0]
	v_pk_mul_f32 v[178:179], v[194:195], v[178:179]
	v_pk_mul_f32 v[176:177], v[192:193], v[176:177]
	v_pk_fma_f32 v[178:179], v[10:11], v[178:179], v[2:3]
	v_pk_fma_f32 v[176:177], v[8:9], v[176:177], v[0:1]
	v_pk_mul_f32 v[182:183], v[182:183], v[78:79] op_sel_hi:[1, 0]
	v_cvt_pk_bf16_f32 v176, v176, v177
	v_cvt_pk_bf16_f32 v177, v178, v179
	global_store_dwordx2 v[76:77], v[176:177], off
	v_pk_mul_f32 v[180:181], v[180:181], v[78:79] op_sel_hi:[1, 0]
	v_pk_mul_f32 v[178:179], v[198:199], v[182:183]
	v_pk_mul_f32 v[176:177], v[196:197], v[180:181]
	v_pk_fma_f32 v[178:179], v[14:15], v[178:179], v[6:7]
	v_pk_fma_f32 v[176:177], v[12:13], v[176:177], v[4:5]
	v_pk_mul_f32 v[180:181], v[186:187], v[78:79] op_sel_hi:[1, 0]
	v_cvt_pk_bf16_f32 v176, v176, v177
	v_cvt_pk_bf16_f32 v177, v178, v179
	global_store_dwordx2 v[76:77], v[176:177], off offset:512
	v_pk_mul_f32 v[182:183], v[184:185], v[78:79] op_sel_hi:[1, 0]
	v_pk_mul_f32 v[178:179], v[246:247], v[180:181]
	v_pk_mul_f32 v[176:177], v[244:245], v[182:183]
	v_pk_fma_f32 v[178:179], v[26:27], v[178:179], v[18:19]
	v_pk_fma_f32 v[176:177], v[24:25], v[176:177], v[16:17]
	v_pk_mul_f32 v[180:181], v[190:191], v[78:79] op_sel_hi:[1, 0]
	v_cvt_pk_bf16_f32 v176, v176, v177
	v_cvt_pk_bf16_f32 v177, v178, v179
	global_store_dwordx2 v[76:77], v[176:177], off offset:1024
	v_pk_mul_f32 v[182:183], v[188:189], v[78:79] op_sel_hi:[1, 0]
	v_pk_mul_f32 v[178:179], v[250:251], v[180:181]
	v_pk_mul_f32 v[176:177], v[248:249], v[182:183]
	v_pk_fma_f32 v[178:179], v[30:31], v[178:179], v[22:23]
	v_pk_fma_f32 v[176:177], v[28:29], v[176:177], v[20:21]
	s_nop 0
	v_cvt_pk_bf16_f32 v176, v176, v177
	v_cvt_pk_bf16_f32 v177, v178, v179
	global_store_dwordx2 v[76:77], v[176:177], off offset:1536
	v_lshl_add_u64 v[76:77], v[42:43], 0, s[6:7]
	v_add_co_u32_e64 v76, s[0:1], s10, v76
	s_add_u32 s6, s6, 0x800
	s_nop 0
	v_addc_co_u32_e64 v77, s[0:1], 0, v77, s[0:1]
	s_addc_u32 s7, s7, 0
	v_lshl_add_u64 v[44:45], v[44:45], 0, s[4:5]
	s_cmpk_eq_i32 s6, 0x4000
	s_waitcnt vmcnt(28)
	v_pk_mul_f32 v[78:79], v[214:215], v[214:215]
	v_pk_mul_f32 v[80:81], v[212:213], v[212:213]
	v_pk_mul_f32 v[82:83], v[218:219], v[218:219]
	v_pk_mul_f32 v[84:85], v[216:217], v[216:217]
	v_pk_mov_b32 v[90:91], v[80:81], v[78:79] op_sel:[1, 0]
	v_mov_b32_e32 v81, v79
	v_pk_mov_b32 v[78:79], v[84:85], v[82:83] op_sel:[1, 0]
	v_mov_b32_e32 v85, v83
	v_mul_f32_e32 v89, v224, v224
	v_mul_f32_e32 v86, v221, v221
	v_mul_f32_e32 v88, v223, v223
	v_pk_add_f32 v[80:81], v[90:91], v[80:81]
	v_pk_add_f32 v[78:79], v[78:79], v[84:85]
	v_mul_f32_e32 v92, v225, v225
	v_mul_f32_e32 v93, v226, v226
	v_mul_f32_e32 v94, v227, v227
	v_pk_fma_f32 v[82:83], v[220:221], v[220:221], v[86:87] op_sel_hi:[1, 1, 0]
	v_pk_fma_f32 v[86:87], v[222:223], v[222:223], v[88:89] op_sel_hi:[1, 1, 0]
	v_pk_add_f32 v[80:81], v[80:81], v[80:81] op_sel:[0, 1] op_sel_hi:[1, 0]
	v_pk_add_f32 v[78:79], v[78:79], v[78:79] op_sel:[0, 1] op_sel_hi:[1, 0]
	v_mov_b32_e32 v83, v93
	v_mov_b32_e32 v87, v94
	v_mov_b32_e32 v81, v89
	v_mov_b32_e32 v79, v92
	v_pk_add_f32 v[82:83], v[82:83], v[86:87]
	v_pk_add_f32 v[78:79], v[80:81], v[78:79]
	s_nop 0
	v_pk_add_f32 v[78:79], v[78:79], v[82:83]
	s_nop 0
	v_add_f32_e32 v78, v78, v79
	s_waitcnt lgkmcnt(0)
	s_nop 1
	v_add_f32_dpp v78, v78, v78 quad_perm:[1, 0, 3, 2] row_mask:0xf bank_mask:0xf
	s_nop 1
	v_add_f32_dpp v78, v78, v78 quad_perm:[2, 3, 0, 1] row_mask:0xf bank_mask:0xf
	s_nop 1
	v_add_f32_dpp v78, v78, v78 row_half_mirror row_mask:0xf bank_mask:0xf
	s_nop 1
	v_add_f32_dpp v78, v78, v78 row_mirror row_mask:0xf bank_mask:0xf
	ds_bpermute_b32 v79, v51, v78
	s_waitcnt lgkmcnt(0)
	v_add_f32_e32 v78, v78, v79
	v_mov_b32_e32 v79, v78
	s_nop 1
	v_permlane32_swap_b32_e32 v79, v78
	v_add_f32_e32 v78, v78, v79
	v_fmamk_f32 v78, v78, 0x3a800000, v55
	v_mul_f32_e32 v79, 0x4b800000, v78
	v_cmp_gt_f32_e64 s[0:1], s9, v78
	s_nop 1
	v_cndmask_b32_e64 v78, v78, v79, s[0:1]
	v_rsq_f32_e32 v78, v78
	s_nop 0
	v_mul_f32_e32 v79, 0x45800000, v78
	v_cndmask_b32_e64 v78, v78, v79, s[0:1]
	v_pk_mul_f32 v[214:215], v[214:215], v[78:79] op_sel_hi:[1, 0]
	v_pk_mul_f32 v[212:213], v[212:213], v[78:79] op_sel_hi:[1, 0]
	v_pk_mul_f32 v[214:215], v[194:195], v[214:215]
	v_pk_mul_f32 v[212:213], v[192:193], v[212:213]
	v_pk_fma_f32 v[214:215], v[10:11], v[214:215], v[2:3]
	v_pk_fma_f32 v[212:213], v[8:9], v[212:213], v[0:1]
	v_pk_mul_f32 v[218:219], v[218:219], v[78:79] op_sel_hi:[1, 0]
	v_cvt_pk_bf16_f32 v212, v212, v213
	v_cvt_pk_bf16_f32 v213, v214, v215
	global_store_dwordx2 v[76:77], v[212:213], off
	v_pk_mul_f32 v[216:217], v[216:217], v[78:79] op_sel_hi:[1, 0]
	v_pk_mul_f32 v[214:215], v[198:199], v[218:219]
	v_pk_mul_f32 v[212:213], v[196:197], v[216:217]
	v_pk_fma_f32 v[214:215], v[14:15], v[214:215], v[6:7]
	v_pk_fma_f32 v[212:213], v[12:13], v[212:213], v[4:5]
	v_pk_mul_f32 v[216:217], v[222:223], v[78:79] op_sel_hi:[1, 0]
	v_cvt_pk_bf16_f32 v212, v212, v213
	v_cvt_pk_bf16_f32 v213, v214, v215
	global_store_dwordx2 v[76:77], v[212:213], off offset:512
	v_pk_mul_f32 v[218:219], v[220:221], v[78:79] op_sel_hi:[1, 0]
	v_pk_mul_f32 v[214:215], v[246:247], v[216:217]
	v_pk_mul_f32 v[212:213], v[244:245], v[218:219]
	v_pk_fma_f32 v[214:215], v[26:27], v[214:215], v[18:19]
	v_pk_fma_f32 v[212:213], v[24:25], v[212:213], v[16:17]
	v_pk_mul_f32 v[216:217], v[226:227], v[78:79] op_sel_hi:[1, 0]
	v_cvt_pk_bf16_f32 v212, v212, v213
	v_cvt_pk_bf16_f32 v213, v214, v215
	global_store_dwordx2 v[76:77], v[212:213], off offset:1024
	v_pk_mul_f32 v[218:219], v[224:225], v[78:79] op_sel_hi:[1, 0]
	v_pk_mul_f32 v[214:215], v[250:251], v[216:217]
	v_pk_mul_f32 v[212:213], v[248:249], v[218:219]
	v_pk_fma_f32 v[214:215], v[30:31], v[214:215], v[22:23]
	v_pk_fma_f32 v[212:213], v[28:29], v[212:213], v[20:21]
	s_nop 0
	v_cvt_pk_bf16_f32 v212, v212, v213
	v_cvt_pk_bf16_f32 v213, v214, v215
	global_store_dwordx2 v[76:77], v[212:213], off offset:1536
	v_lshl_add_u64 v[76:77], v[42:43], 0, s[6:7]
	v_add_co_u32_e64 v76, s[0:1], s10, v76
	s_add_u32 s6, s6, 0x800
	s_nop 0
	v_addc_co_u32_e64 v77, s[0:1], 0, v77, s[0:1]
	s_addc_u32 s7, s7, 0
	v_lshl_add_u64 v[44:45], v[44:45], 0, s[4:5]
	s_cmpk_eq_i32 s6, 0x4000
	s_waitcnt vmcnt(28)
	v_pk_mul_f32 v[78:79], v[230:231], v[230:231]
	v_pk_mul_f32 v[80:81], v[228:229], v[228:229]
	v_pk_mul_f32 v[82:83], v[234:235], v[234:235]
	v_pk_mul_f32 v[84:85], v[232:233], v[232:233]
	v_pk_mov_b32 v[90:91], v[80:81], v[78:79] op_sel:[1, 0]
	v_mov_b32_e32 v81, v79
	v_pk_mov_b32 v[78:79], v[84:85], v[82:83] op_sel:[1, 0]
	v_mov_b32_e32 v85, v83
	v_mul_f32_e32 v89, v240, v240
	v_mul_f32_e32 v86, v237, v237
	v_mul_f32_e32 v88, v239, v239
	v_pk_add_f32 v[80:81], v[90:91], v[80:81]
	v_pk_add_f32 v[78:79], v[78:79], v[84:85]
	v_mul_f32_e32 v92, v241, v241
	v_mul_f32_e32 v93, v242, v242
	v_mul_f32_e32 v94, v243, v243
	v_pk_fma_f32 v[82:83], v[236:237], v[236:237], v[86:87] op_sel_hi:[1, 1, 0]
	v_pk_fma_f32 v[86:87], v[238:239], v[238:239], v[88:89] op_sel_hi:[1, 1, 0]
	v_pk_add_f32 v[80:81], v[80:81], v[80:81] op_sel:[0, 1] op_sel_hi:[1, 0]
	v_pk_add_f32 v[78:79], v[78:79], v[78:79] op_sel:[0, 1] op_sel_hi:[1, 0]
	v_mov_b32_e32 v83, v93
	v_mov_b32_e32 v87, v94
	v_mov_b32_e32 v81, v89
	v_mov_b32_e32 v79, v92
	v_pk_add_f32 v[82:83], v[82:83], v[86:87]
	v_pk_add_f32 v[78:79], v[80:81], v[78:79]
	s_nop 0
	v_pk_add_f32 v[78:79], v[78:79], v[82:83]
	s_nop 0
	v_add_f32_e32 v78, v78, v79
	s_waitcnt lgkmcnt(0)
	s_nop 1
	v_add_f32_dpp v78, v78, v78 quad_perm:[1, 0, 3, 2] row_mask:0xf bank_mask:0xf
	s_nop 1
	v_add_f32_dpp v78, v78, v78 quad_perm:[2, 3, 0, 1] row_mask:0xf bank_mask:0xf
	s_nop 1
	v_add_f32_dpp v78, v78, v78 row_half_mirror row_mask:0xf bank_mask:0xf
	s_nop 1
	v_add_f32_dpp v78, v78, v78 row_mirror row_mask:0xf bank_mask:0xf
	ds_bpermute_b32 v79, v51, v78
	s_waitcnt lgkmcnt(0)
	v_add_f32_e32 v78, v78, v79
	v_mov_b32_e32 v79, v78
	s_nop 1
	v_permlane32_swap_b32_e32 v79, v78
	v_add_f32_e32 v78, v78, v79
	v_fmamk_f32 v78, v78, 0x3a800000, v55
	v_mul_f32_e32 v79, 0x4b800000, v78
	v_cmp_gt_f32_e64 s[0:1], s9, v78
	s_nop 1
	v_cndmask_b32_e64 v78, v78, v79, s[0:1]
	v_rsq_f32_e32 v78, v78
	s_nop 0
	v_mul_f32_e32 v79, 0x45800000, v78
	v_cndmask_b32_e64 v78, v78, v79, s[0:1]
	v_pk_mul_f32 v[230:231], v[230:231], v[78:79] op_sel_hi:[1, 0]
	v_pk_mul_f32 v[228:229], v[228:229], v[78:79] op_sel_hi:[1, 0]
	v_pk_mul_f32 v[230:231], v[194:195], v[230:231]
	v_pk_mul_f32 v[228:229], v[192:193], v[228:229]
	v_pk_fma_f32 v[230:231], v[10:11], v[230:231], v[2:3]
	v_pk_fma_f32 v[228:229], v[8:9], v[228:229], v[0:1]
	v_pk_mul_f32 v[234:235], v[234:235], v[78:79] op_sel_hi:[1, 0]
	v_cvt_pk_bf16_f32 v228, v228, v229
	v_cvt_pk_bf16_f32 v229, v230, v231
	global_store_dwordx2 v[76:77], v[228:229], off
	v_pk_mul_f32 v[232:233], v[232:233], v[78:79] op_sel_hi:[1, 0]
	v_pk_mul_f32 v[230:231], v[198:199], v[234:235]
	v_pk_mul_f32 v[228:229], v[196:197], v[232:233]
	v_pk_fma_f32 v[230:231], v[14:15], v[230:231], v[6:7]
	v_pk_fma_f32 v[228:229], v[12:13], v[228:229], v[4:5]
	v_pk_mul_f32 v[232:233], v[238:239], v[78:79] op_sel_hi:[1, 0]
	v_cvt_pk_bf16_f32 v228, v228, v229
	v_cvt_pk_bf16_f32 v229, v230, v231
	global_store_dwordx2 v[76:77], v[228:229], off offset:512
	v_pk_mul_f32 v[234:235], v[236:237], v[78:79] op_sel_hi:[1, 0]
	v_pk_mul_f32 v[230:231], v[246:247], v[232:233]
	v_pk_mul_f32 v[228:229], v[244:245], v[234:235]
	v_pk_fma_f32 v[230:231], v[26:27], v[230:231], v[18:19]
	v_pk_fma_f32 v[228:229], v[24:25], v[228:229], v[16:17]
	v_pk_mul_f32 v[232:233], v[242:243], v[78:79] op_sel_hi:[1, 0]
	v_cvt_pk_bf16_f32 v228, v228, v229
	v_cvt_pk_bf16_f32 v229, v230, v231
	global_store_dwordx2 v[76:77], v[228:229], off offset:1024
	v_pk_mul_f32 v[234:235], v[240:241], v[78:79] op_sel_hi:[1, 0]
	v_pk_mul_f32 v[230:231], v[250:251], v[232:233]
	v_pk_mul_f32 v[228:229], v[248:249], v[234:235]
	v_pk_fma_f32 v[230:231], v[30:31], v[230:231], v[22:23]
	v_pk_fma_f32 v[228:229], v[28:29], v[228:229], v[20:21]
	s_nop 0
	v_cvt_pk_bf16_f32 v228, v228, v229
	v_cvt_pk_bf16_f32 v229, v230, v231
	global_store_dwordx2 v[76:77], v[228:229], off offset:1536
	s_add_i32 s11, s11, s92
	s_add_i32 s2, s2, s8
	s_cmpk_gt_i32 s11, 0xff
	s_cbranch_scc0 .LBB0_225
